# v27 + code placement: the ten hot loop heads (7 GEMM K-loops, attention tile loop, both S5 step loops) on 64-byte boundaries (.p2align 6)
# speedup vs baseline: 1.0040x; 1.0040x over previous
; template <class Epi, class Sched, bool ALIGN_EPI = false, bool SP2 = false>
; __device__ __forceinline__ void gemm_phase(PG8_LAS unsigned char* lds, const Gemm g, const Sched& S, const Epi& E, int tid_in) {
;     ...
;         const bool has_next = S.next(ui + 1, nxt);
;         const char* nA = has_next ? (const char*)g.A + (size_t)nxt.pm * tstep : cA; const char* nB = has_next ? (const char*)g.Bt + (size_t)nxt.pn * tstep : cB;
;         for (int t = 0; t < nt; t += 2) {
;             const bool last = (t == nt - 2);
;             const char* a1 = cA + (size_t)(t + 1) * kstep;
;             const char* a2 = last ? nA : cA + (size_t)(t + 2) * kstep; const char* b2 = last ? nB : cB + (size_t)(t + 2) * kstep;
;             const char* a3 = a2 + kstep; const char* b3 = b2 + kstep;
;     ...
; #pragma unroll
;         for (int a = 0; a < 2; ++a)
; #pragma unroll
;             for (int b = 0; b < 2; ++b)
; #pragma unroll
;                 for (int m = 0; m < 4; ++m)
; #pragma unroll
;                     for (int n = 0; n < 2; ++n) acc[a][b][m][n] = (f32x4){0.f, 0.f, 0.f, 0.f};
.LBB0_115:
	s_ashr_i32 s53, s52, 31
	s_lshl_b64 s[58:59], s[52:53], 19
	s_add_u32 s58, s26, s58
	s_addc_u32 s59, s27, s59
	s_and_b64 s[60:61], s[0:1], exec
	s_cselect_b32 s53, s59, s7
	s_cselect_b32 s87, s58, s6
	s_ashr_i32 s43, s42, 31
	s_lshl_b64 s[60:61], s[42:43], 19
	s_add_u32 s60, s30, s60
	s_addc_u32 s61, s31, s61
	s_and_b64 s[70:71], s[0:1], exec
	s_cselect_b32 s43, s61, s67
	s_cselect_b32 s88, s60, s66
	s_add_u32 s6, s6, 0x40080
	s_addc_u32 s7, s7, 0
	s_add_u32 s89, s66, 0x100
	v_mov_b32_e32 v0, 0
	s_addc_u32 s90, s67, 0
	s_mov_b32 s91, -2
	v_mov_b32_e32 v1, v0
	v_mov_b32_e32 v2, v0
	v_mov_b32_e32 v3, v0
	v_mov_b32_e32 v4, v0
	v_mov_b32_e32 v5, v0
	v_mov_b32_e32 v6, v0
	v_mov_b32_e32 v7, v0
	v_mov_b32_e32 v16, v0
	v_mov_b32_e32 v17, v0
	v_mov_b32_e32 v18, v0
	v_mov_b32_e32 v19, v0
	v_mov_b32_e32 v20, v0
	v_mov_b32_e32 v21, v0
	v_mov_b32_e32 v22, v0
	v_mov_b32_e32 v23, v0
	v_mov_b32_e32 v32, v0
	v_mov_b32_e32 v33, v0
	v_mov_b32_e32 v34, v0
	v_mov_b32_e32 v35, v0
	v_mov_b32_e32 v36, v0
	v_mov_b32_e32 v37, v0
	v_mov_b32_e32 v38, v0
	v_mov_b32_e32 v39, v0
	v_mov_b32_e32 v48, v0
	v_mov_b32_e32 v49, v0
	v_mov_b32_e32 v50, v0
	v_mov_b32_e32 v51, v0
	v_mov_b32_e32 v52, v0
	v_mov_b32_e32 v53, v0
	v_mov_b32_e32 v54, v0
	v_mov_b32_e32 v55, v0
	v_mov_b32_e32 v8, v0
	v_mov_b32_e32 v9, v0
	v_mov_b32_e32 v10, v0
	v_mov_b32_e32 v11, v0
	v_mov_b32_e32 v12, v0
	v_mov_b32_e32 v13, v0
	v_mov_b32_e32 v14, v0
	v_mov_b32_e32 v15, v0
	v_mov_b32_e32 v24, v0
	v_mov_b32_e32 v25, v0
	v_mov_b32_e32 v26, v0
	v_mov_b32_e32 v27, v0
	v_mov_b32_e32 v28, v0
	v_mov_b32_e32 v29, v0
	v_mov_b32_e32 v30, v0
	v_mov_b32_e32 v31, v0
	v_mov_b32_e32 v40, v0
	v_mov_b32_e32 v41, v0
	v_mov_b32_e32 v42, v0
	v_mov_b32_e32 v43, v0
	v_mov_b32_e32 v44, v0
	v_mov_b32_e32 v45, v0
	v_mov_b32_e32 v46, v0
	v_mov_b32_e32 v47, v0
	v_mov_b32_e32 v56, v0
	v_mov_b32_e32 v57, v0
	v_mov_b32_e32 v58, v0
	v_mov_b32_e32 v59, v0
	v_mov_b32_e32 v60, v0
	v_mov_b32_e32 v61, v0
	v_mov_b32_e32 v62, v0
	v_mov_b32_e32 v63, v0
	v_mov_b32_e32 v64, v0
	v_mov_b32_e32 v65, v0
	v_mov_b32_e32 v66, v0
	v_mov_b32_e32 v67, v0
	v_mov_b32_e32 v68, v0
	v_mov_b32_e32 v69, v0
	v_mov_b32_e32 v70, v0
	v_mov_b32_e32 v71, v0
	v_mov_b32_e32 v80, v0
	v_mov_b32_e32 v81, v0
	v_mov_b32_e32 v82, v0
	v_mov_b32_e32 v83, v0
	v_mov_b32_e32 v84, v0
	v_mov_b32_e32 v85, v0
	v_mov_b32_e32 v86, v0
	v_mov_b32_e32 v87, v0
	v_mov_b32_e32 v96, v0
	v_mov_b32_e32 v97, v0
	v_mov_b32_e32 v98, v0
	v_mov_b32_e32 v99, v0
	v_mov_b32_e32 v100, v0
	v_mov_b32_e32 v101, v0
	v_mov_b32_e32 v102, v0
	v_mov_b32_e32 v103, v0
	v_mov_b32_e32 v112, v0
	v_mov_b32_e32 v113, v0
	v_mov_b32_e32 v114, v0
	v_mov_b32_e32 v115, v0
	v_mov_b32_e32 v116, v0
	v_mov_b32_e32 v117, v0
	v_mov_b32_e32 v118, v0
	v_mov_b32_e32 v119, v0
	v_mov_b32_e32 v72, v0
	v_mov_b32_e32 v73, v0
	v_mov_b32_e32 v74, v0
	v_mov_b32_e32 v75, v0
	v_mov_b32_e32 v76, v0
	v_mov_b32_e32 v77, v0
	v_mov_b32_e32 v78, v0
	v_mov_b32_e32 v79, v0
	v_mov_b32_e32 v88, v0
	v_mov_b32_e32 v89, v0
	v_mov_b32_e32 v90, v0
	v_mov_b32_e32 v91, v0
	v_mov_b32_e32 v92, v0
	v_mov_b32_e32 v93, v0
	v_mov_b32_e32 v94, v0
	v_mov_b32_e32 v95, v0
	v_mov_b32_e32 v104, v0
	v_mov_b32_e32 v105, v0
	v_mov_b32_e32 v106, v0
	v_mov_b32_e32 v107, v0
	v_mov_b32_e32 v108, v0
	v_mov_b32_e32 v109, v0
	v_mov_b32_e32 v110, v0
	v_mov_b32_e32 v111, v0
	v_mov_b32_e32 v120, v0
	v_mov_b32_e32 v121, v0
	v_mov_b32_e32 v122, v0
	v_mov_b32_e32 v123, v0
	v_mov_b32_e32 v124, v0
	v_mov_b32_e32 v125, v0
	v_mov_b32_e32 v126, v0
	v_mov_b32_e32 v127, v0
	.p2align 6

; template <class Epi, class Sched, bool ALIGN_EPI = false, bool SP2 = false>
; __device__ __forceinline__ void gemm_phase(PG8_LAS unsigned char* lds, const Gemm g, const Sched& S, const Epi& E, int tid_in) {
;     ...
;         const bool has_next = S.next(ui + 1, nxt);
;         const char* nA = has_next ? (const char*)g.A + (size_t)nxt.pm * tstep : cA; const char* nB = has_next ? (const char*)g.Bt + (size_t)nxt.pn * tstep : cB;
;         for (int t = 0; t < nt; t += 2) {
;             const bool last = (t == nt - 2);
;             const char* a1 = cA + (size_t)(t + 1) * kstep;
;             const char* a2 = last ? nA : cA + (size_t)(t + 2) * kstep; const char* b2 = last ? nB : cB + (size_t)(t + 2) * kstep;
;             const char* a3 = a2 + kstep; const char* b3 = b2 + kstep;
;     ...
; #pragma unroll
;         for (int a = 0; a < 2; ++a)
; #pragma unroll
;             for (int b = 0; b < 2; ++b)
; #pragma unroll
;                 for (int m = 0; m < 4; ++m)
; #pragma unroll
;                     for (int n = 0; n < 2; ++n) acc[a][b][m][n] = (f32x4){0.f, 0.f, 0.f, 0.f};
.LBB0_165:
	s_ashr_i32 s59, s58, 31
	s_lshl_b64 s[60:61], s[58:59], 19
	s_add_u32 s60, s26, s60
	s_addc_u32 s61, s27, s61
	s_and_b64 s[62:63], s[8:9], exec
	s_cselect_b32 s59, s61, s7
	s_cselect_b32 s91, s60, s6
	s_ashr_i32 s53, s52, 31
	s_lshl_b64 s[62:63], s[52:53], 19
	s_add_u32 s62, s69, s62
	s_addc_u32 s63, s74, s63
	s_and_b64 s[72:73], s[8:9], exec
	s_cselect_b32 s53, s63, s71
	s_cselect_b32 s92, s62, s70
	s_add_u32 s6, s6, 0x40080
	s_addc_u32 s7, s7, 0
	s_add_u32 s93, s70, 0x100
	v_mov_b32_e32 v0, 0
	s_addc_u32 s94, s71, 0
	s_mov_b32 s95, -2
	v_mov_b32_e32 v1, v0
	v_mov_b32_e32 v2, v0
	v_mov_b32_e32 v3, v0
	v_mov_b32_e32 v4, v0
	v_mov_b32_e32 v5, v0
	v_mov_b32_e32 v6, v0
	v_mov_b32_e32 v7, v0
	v_mov_b32_e32 v16, v0
	v_mov_b32_e32 v17, v0
	v_mov_b32_e32 v18, v0
	v_mov_b32_e32 v19, v0
	v_mov_b32_e32 v20, v0
	v_mov_b32_e32 v21, v0
	v_mov_b32_e32 v22, v0
	v_mov_b32_e32 v23, v0
	v_mov_b32_e32 v32, v0
	v_mov_b32_e32 v33, v0
	v_mov_b32_e32 v34, v0
	v_mov_b32_e32 v35, v0
	v_mov_b32_e32 v36, v0
	v_mov_b32_e32 v37, v0
	v_mov_b32_e32 v38, v0
	v_mov_b32_e32 v39, v0
	v_mov_b32_e32 v48, v0
	v_mov_b32_e32 v49, v0
	v_mov_b32_e32 v50, v0
	v_mov_b32_e32 v51, v0
	v_mov_b32_e32 v52, v0
	v_mov_b32_e32 v53, v0
	v_mov_b32_e32 v54, v0
	v_mov_b32_e32 v55, v0
	v_mov_b32_e32 v8, v0
	v_mov_b32_e32 v9, v0
	v_mov_b32_e32 v10, v0
	v_mov_b32_e32 v11, v0
	v_mov_b32_e32 v12, v0
	v_mov_b32_e32 v13, v0
	v_mov_b32_e32 v14, v0
	v_mov_b32_e32 v15, v0
	v_mov_b32_e32 v24, v0
	v_mov_b32_e32 v25, v0
	v_mov_b32_e32 v26, v0
	v_mov_b32_e32 v27, v0
	v_mov_b32_e32 v28, v0
	v_mov_b32_e32 v29, v0
	v_mov_b32_e32 v30, v0
	v_mov_b32_e32 v31, v0
	v_mov_b32_e32 v40, v0
	v_mov_b32_e32 v41, v0
	v_mov_b32_e32 v42, v0
	v_mov_b32_e32 v43, v0
	v_mov_b32_e32 v44, v0
	v_mov_b32_e32 v45, v0
	v_mov_b32_e32 v46, v0
	v_mov_b32_e32 v47, v0
	v_mov_b32_e32 v56, v0
	v_mov_b32_e32 v57, v0
	v_mov_b32_e32 v58, v0
	v_mov_b32_e32 v59, v0
	v_mov_b32_e32 v60, v0
	v_mov_b32_e32 v61, v0
	v_mov_b32_e32 v62, v0
	v_mov_b32_e32 v63, v0
	v_mov_b32_e32 v64, v0
	v_mov_b32_e32 v65, v0
	v_mov_b32_e32 v66, v0
	v_mov_b32_e32 v67, v0
	v_mov_b32_e32 v68, v0
	v_mov_b32_e32 v69, v0
	v_mov_b32_e32 v70, v0
	v_mov_b32_e32 v71, v0
	v_mov_b32_e32 v80, v0
	v_mov_b32_e32 v81, v0
	v_mov_b32_e32 v82, v0
	v_mov_b32_e32 v83, v0
	v_mov_b32_e32 v84, v0
	v_mov_b32_e32 v85, v0
	v_mov_b32_e32 v86, v0
	v_mov_b32_e32 v87, v0
	v_mov_b32_e32 v96, v0
	v_mov_b32_e32 v97, v0
	v_mov_b32_e32 v98, v0
	v_mov_b32_e32 v99, v0
	v_mov_b32_e32 v100, v0
	v_mov_b32_e32 v101, v0
	v_mov_b32_e32 v102, v0
	v_mov_b32_e32 v103, v0
	v_mov_b32_e32 v112, v0
	v_mov_b32_e32 v113, v0
	v_mov_b32_e32 v114, v0
	v_mov_b32_e32 v115, v0
	v_mov_b32_e32 v116, v0
	v_mov_b32_e32 v117, v0
	v_mov_b32_e32 v118, v0
	v_mov_b32_e32 v119, v0
	v_mov_b32_e32 v72, v0
	v_mov_b32_e32 v73, v0
	v_mov_b32_e32 v74, v0
	v_mov_b32_e32 v75, v0
	v_mov_b32_e32 v76, v0
	v_mov_b32_e32 v77, v0
	v_mov_b32_e32 v78, v0
	v_mov_b32_e32 v79, v0
	v_mov_b32_e32 v88, v0
	v_mov_b32_e32 v89, v0
	v_mov_b32_e32 v90, v0
	v_mov_b32_e32 v91, v0
	v_mov_b32_e32 v92, v0
	v_mov_b32_e32 v93, v0
	v_mov_b32_e32 v94, v0
	v_mov_b32_e32 v95, v0
	v_mov_b32_e32 v104, v0
	v_mov_b32_e32 v105, v0
	v_mov_b32_e32 v106, v0
	v_mov_b32_e32 v107, v0
	v_mov_b32_e32 v108, v0
	v_mov_b32_e32 v109, v0
	v_mov_b32_e32 v110, v0
	v_mov_b32_e32 v111, v0
	v_mov_b32_e32 v120, v0
	v_mov_b32_e32 v121, v0
	v_mov_b32_e32 v122, v0
	v_mov_b32_e32 v123, v0
	v_mov_b32_e32 v124, v0
	v_mov_b32_e32 v125, v0
	v_mov_b32_e32 v126, v0
	v_mov_b32_e32 v127, v0
	.p2align 6

; template <class Epi, class Sched, bool ALIGN_EPI = false, bool SP2 = false>
; __device__ __forceinline__ void gemm_phase(PG8_LAS unsigned char* lds, const Gemm g, const Sched& S, const Epi& E, int tid_in) {
;     ...
;         const bool has_next = S.next(ui + 1, nxt);
;         const char* nA = has_next ? (const char*)g.A + (size_t)nxt.pm * tstep : cA; const char* nB = has_next ? (const char*)g.Bt + (size_t)nxt.pn * tstep : cB;
;         for (int t = 0; t < nt; t += 2) {
;             const bool last = (t == nt - 2);
;             const char* a1 = cA + (size_t)(t + 1) * kstep;
;             const char* a2 = last ? nA : cA + (size_t)(t + 2) * kstep; const char* b2 = last ? nB : cB + (size_t)(t + 2) * kstep;
;             const char* a3 = a2 + kstep; const char* b3 = b2 + kstep;
;     ...
; #pragma unroll
;         for (int a = 0; a < 2; ++a)
; #pragma unroll
;             for (int b = 0; b < 2; ++b)
; #pragma unroll
;                 for (int m = 0; m < 4; ++m)
; #pragma unroll
;                     for (int n = 0; n < 2; ++n) acc[a][b][m][n] = (f32x4){0.f, 0.f, 0.f, 0.f};
.LBB0_213:
	s_ashr_i32 s43, s42, 31
	s_lshl_b64 s[52:53], s[42:43], 19
	s_add_u32 s52, s70, s52
	s_addc_u32 s53, s71, s53
	s_and_b64 s[58:59], s[6:7], exec
	s_cselect_b32 s43, s53, s63
	s_cselect_b32 s87, s52, s62
	s_ashr_i32 s41, s40, 31
	s_lshl_b64 s[58:59], s[40:41], 19
	s_add_u32 s58, s26, s58
	s_addc_u32 s59, s27, s59
	s_and_b64 s[66:67], s[6:7], exec
	s_cselect_b32 s41, s59, s65
	s_cselect_b32 s88, s58, s64
	s_add_u32 s62, s62, 0x40080
	s_addc_u32 s63, s63, 0
	s_add_u32 s89, s64, 0x100
	v_mov_b32_e32 v0, 0
	s_addc_u32 s90, s65, 0
	s_mov_b32 s91, -2
	v_mov_b32_e32 v1, v0
	v_mov_b32_e32 v2, v0
	v_mov_b32_e32 v3, v0
	v_mov_b32_e32 v4, v0
	v_mov_b32_e32 v5, v0
	v_mov_b32_e32 v6, v0
	v_mov_b32_e32 v7, v0
	v_mov_b32_e32 v8, v0
	v_mov_b32_e32 v9, v0
	v_mov_b32_e32 v10, v0
	v_mov_b32_e32 v11, v0
	v_mov_b32_e32 v16, v0
	v_mov_b32_e32 v17, v0
	v_mov_b32_e32 v18, v0
	v_mov_b32_e32 v19, v0
	v_mov_b32_e32 v24, v0
	v_mov_b32_e32 v25, v0
	v_mov_b32_e32 v26, v0
	v_mov_b32_e32 v27, v0
	v_mov_b32_e32 v32, v0
	v_mov_b32_e32 v33, v0
	v_mov_b32_e32 v34, v0
	v_mov_b32_e32 v35, v0
	v_mov_b32_e32 v40, v0
	v_mov_b32_e32 v41, v0
	v_mov_b32_e32 v42, v0
	v_mov_b32_e32 v43, v0
	v_mov_b32_e32 v48, v0
	v_mov_b32_e32 v49, v0
	v_mov_b32_e32 v50, v0
	v_mov_b32_e32 v51, v0
	v_mov_b32_e32 v12, v0
	v_mov_b32_e32 v13, v0
	v_mov_b32_e32 v14, v0
	v_mov_b32_e32 v15, v0
	v_mov_b32_e32 v20, v0
	v_mov_b32_e32 v21, v0
	v_mov_b32_e32 v22, v0
	v_mov_b32_e32 v23, v0
	v_mov_b32_e32 v28, v0
	v_mov_b32_e32 v29, v0
	v_mov_b32_e32 v30, v0
	v_mov_b32_e32 v31, v0
	v_mov_b32_e32 v36, v0
	v_mov_b32_e32 v37, v0
	v_mov_b32_e32 v38, v0
	v_mov_b32_e32 v39, v0
	v_mov_b32_e32 v44, v0
	v_mov_b32_e32 v45, v0
	v_mov_b32_e32 v46, v0
	v_mov_b32_e32 v47, v0
	v_mov_b32_e32 v52, v0
	v_mov_b32_e32 v53, v0
	v_mov_b32_e32 v54, v0
	v_mov_b32_e32 v55, v0
	v_mov_b32_e32 v56, v0
	v_mov_b32_e32 v57, v0
	v_mov_b32_e32 v58, v0
	v_mov_b32_e32 v59, v0
	v_mov_b32_e32 v60, v0
	v_mov_b32_e32 v61, v0
	v_mov_b32_e32 v62, v0
	v_mov_b32_e32 v63, v0
	v_mov_b32_e32 v64, v0
	v_mov_b32_e32 v65, v0
	v_mov_b32_e32 v66, v0
	v_mov_b32_e32 v67, v0
	v_mov_b32_e32 v68, v0
	v_mov_b32_e32 v69, v0
	v_mov_b32_e32 v70, v0
	v_mov_b32_e32 v71, v0
	v_mov_b32_e32 v72, v0
	v_mov_b32_e32 v73, v0
	v_mov_b32_e32 v74, v0
	v_mov_b32_e32 v75, v0
	v_mov_b32_e32 v80, v0
	v_mov_b32_e32 v81, v0
	v_mov_b32_e32 v82, v0
	v_mov_b32_e32 v83, v0
	v_mov_b32_e32 v88, v0
	v_mov_b32_e32 v89, v0
	v_mov_b32_e32 v90, v0
	v_mov_b32_e32 v91, v0
	v_mov_b32_e32 v96, v0
	v_mov_b32_e32 v97, v0
	v_mov_b32_e32 v98, v0
	v_mov_b32_e32 v99, v0
	v_mov_b32_e32 v104, v0
	v_mov_b32_e32 v105, v0
	v_mov_b32_e32 v106, v0
	v_mov_b32_e32 v107, v0
	v_mov_b32_e32 v112, v0
	v_mov_b32_e32 v113, v0
	v_mov_b32_e32 v114, v0
	v_mov_b32_e32 v115, v0
	v_mov_b32_e32 v76, v0
	v_mov_b32_e32 v77, v0
	v_mov_b32_e32 v78, v0
	v_mov_b32_e32 v79, v0
	v_mov_b32_e32 v84, v0
	v_mov_b32_e32 v85, v0
	v_mov_b32_e32 v86, v0
	v_mov_b32_e32 v87, v0
	v_mov_b32_e32 v92, v0
	v_mov_b32_e32 v93, v0
	v_mov_b32_e32 v94, v0
	v_mov_b32_e32 v95, v0
	v_mov_b32_e32 v100, v0
	v_mov_b32_e32 v101, v0
	v_mov_b32_e32 v102, v0
	v_mov_b32_e32 v103, v0
	v_mov_b32_e32 v108, v0
	v_mov_b32_e32 v109, v0
	v_mov_b32_e32 v110, v0
	v_mov_b32_e32 v111, v0
	v_mov_b32_e32 v116, v0
	v_mov_b32_e32 v117, v0
	v_mov_b32_e32 v118, v0
	v_mov_b32_e32 v119, v0
	v_mov_b32_e32 v120, v0
	v_mov_b32_e32 v121, v0
	v_mov_b32_e32 v122, v0
	v_mov_b32_e32 v123, v0
	v_mov_b32_e32 v124, v0
	v_mov_b32_e32 v125, v0
	v_mov_b32_e32 v126, v0
	v_mov_b32_e32 v127, v0
	.p2align 6

; #define AT_LOADK(tt) do { const unsigned ko = kgo + (unsigned)(tt) * (64 * BR * 2); ks0 = *(const u32x4*)((const char*)K + ko); ks1 = *(const u32x4*)((const char*)K + ko + 32 * BR * 2); } while (0)
; #define AT_LOADV(tt) do { const unsigned vo = vgo + (unsigned)(tt) * 128; vs0 = *(const u32x4*)((const char*)Vt + vo); vs1 = *(const u32x4*)((const char*)Vt + vo + 64 * SEQ * 2); } while (0)
; __device__ __forceinline__ void attn_unit(int b, int h, int qb, bf16_t* Q, const bf16_t* __restrict__ K, const bf16_t* __restrict__ Vt, const bf16_t* __restrict__ Z, const float* __restrict__ hg, float lam, ...
;     ...
;     const float slope2 = __builtin_bit_cast(float, __builtin_amdgcn_readfirstlane(__builtin_bit_cast(int, tab[h])));
;     bf16x8 qf[2][4];
;     { const bf16_t* qp = Q + (rowbase + qw0 + r32) * BR + h * 128 + 8 * hi;
; #pragma unroll
;       for (int sub = 0; sub < 2; ++sub)
; #pragma unroll
;           for (int d0 = 0; d0 < 4; ++d0) qf[sub][d0] = *(const bf16x8*)(qp + sub * 64 + d0 * 16); }
;     const unsigned kgo = (unsigned)(((rowbase + (tid >> 4)) * BR + h * 128 + (tid & 15) * 8) * 2);
;     const int kl = (tid >> 4) * KROW + (tid & 15) * 16;
;     const unsigned vgo = (unsigned)((((size_t)b * BR + h * 128 + (tid >> 3)) * SEQ + (tid & 7) * 8) * 2);
;     const int vl = AT_VOFF + (tid >> 3) * VROW + (tid & 7) * 16;
;     const int NT = 4 * (qb + 1), last_w = (qw0 + 31) >> 6;
;     int tlo_w = 0; if (Dwin < 4096.f) { const int kmin_w = qw0 - (int)Dwin - 1; tlo_w = kmin_w > 0 ? (kmin_w >> 6) : 0; }
;     f32x16 o[2][4];
; #pragma unroll
;     for (int s = 0; s < 2; ++s)
; #pragma unroll
;         for (int d = 0; d < 4; ++d)
; #pragma unroll
;             for (int r = 0; r < 16; ++r) o[s][d][r] = 0.f;
;     float lsum[2] = {0.f, 0.f};
;     u32x4 ks0, ks1, vs0, vs1;
;     ...
;     AT_LOADK(tfirst); AT_LOADV(tfirst); AT_WRITEK(tfirst & 1); AT_WRITEV(tfirst & 1);
;     __syncthreads();
; __device__ __forceinline__ void attn_phase(const Params& P, LAS unsigned char* lds, int bx, int tid_in) {
;     ...
;         const int h = 15 - (u >> 4), qb = 15 - (u & 15);
;         const float Df = tab[16 + h];
;         int tfirst = 0;
;         if (Df < 4096.f) { const int kmin = qb * 256 - (int)Df - 1; tfirst = kmin > 0 ? (kmin >> 6) : 0; }
;         tfirst = __builtin_amdgcn_readfirstlane(tfirst);
.LBB0_243:
	s_or_b64 exec, exec, s[8:9]
	s_ashr_i32 s10, s11, 4
	s_sub_i32 s18, 31, s10
	s_sub_i32 s8, 15, s10
	s_andn2_b32 s11, 15, s11
	s_lshl_b32 s62, s18, 2
	s_add_i32 s62, s62, 0x112c0
	v_mov_b32_e32 v0, s62
	ds_read_b32 v0, v0
	s_lshl_b32 s62, s11, 8
	s_mov_b32 s9, s19
	v_mov_b32_e32 v223, v211
	v_mov_b32_e32 v225, 0
	v_mov_b32_e32 v224, v225
	v_mov_b32_e32 v79, v225
	v_mov_b32_e32 v78, v225
	v_mov_b32_e32 v77, v225
	v_mov_b32_e32 v76, v225
	v_mov_b32_e32 v75, v225
	v_mov_b32_e32 v74, v225
	v_mov_b32_e32 v73, v225
	v_mov_b32_e32 v72, v225
	v_mov_b32_e32 v71, v225
	v_mov_b32_e32 v70, v225
	v_mov_b32_e32 v69, v225
	v_mov_b32_e32 v68, v225
	v_mov_b32_e32 v67, v225
	v_mov_b32_e32 v66, v225
	v_mov_b32_e32 v65, v225
	v_mov_b32_e32 v64, v225
	v_mov_b32_e32 v63, v225
	v_mov_b32_e32 v62, v225
	v_mov_b32_e32 v61, v225
	v_mov_b32_e32 v60, v225
	v_mov_b32_e32 v59, v225
	v_mov_b32_e32 v58, v225
	v_mov_b32_e32 v57, v225
	v_mov_b32_e32 v56, v225
	v_mov_b32_e32 v55, v225
	v_mov_b32_e32 v54, v225
	v_mov_b32_e32 v53, v225
	v_mov_b32_e32 v52, v225
	v_mov_b32_e32 v51, v225
	v_mov_b32_e32 v50, v225
	v_mov_b32_e32 v49, v225
	v_mov_b32_e32 v48, v225
	v_mov_b32_e32 v31, v225
	v_mov_b32_e32 v30, v225
	v_mov_b32_e32 v29, v225
	v_mov_b32_e32 v28, v225
	v_mov_b32_e32 v27, v225
	v_mov_b32_e32 v26, v225
	v_mov_b32_e32 v25, v225
	v_mov_b32_e32 v24, v225
	v_mov_b32_e32 v23, v225
	v_mov_b32_e32 v22, v225
	v_mov_b32_e32 v21, v225
	v_mov_b32_e32 v20, v225
	v_mov_b32_e32 v19, v225
	v_mov_b32_e32 v18, v225
	v_mov_b32_e32 v17, v225
	v_mov_b32_e32 v16, v225
	v_mov_b32_e32 v15, v225
	v_mov_b32_e32 v14, v225
	v_mov_b32_e32 v13, v225
	v_mov_b32_e32 v12, v225
	v_mov_b32_e32 v11, v225
	v_mov_b32_e32 v10, v225
	v_mov_b32_e32 v9, v225
	v_mov_b32_e32 v8, v225
	v_mov_b32_e32 v7, v225
	v_mov_b32_e32 v6, v225
	v_mov_b32_e32 v5, v225
	v_mov_b32_e32 v4, v225
	v_mov_b32_e32 v127, v225
	v_mov_b32_e32 v126, v225
	v_mov_b32_e32 v125, v225
	v_mov_b32_e32 v124, v225
	v_mov_b32_e32 v123, v225
	v_mov_b32_e32 v122, v225
	v_mov_b32_e32 v121, v225
	v_mov_b32_e32 v120, v225
	v_mov_b32_e32 v119, v225
	v_mov_b32_e32 v118, v225
	v_mov_b32_e32 v117, v225
	v_mov_b32_e32 v116, v225
	v_mov_b32_e32 v115, v225
	v_mov_b32_e32 v114, v225
	s_waitcnt lgkmcnt(0)
	v_cvt_i32_f32_e32 v1, v0
	v_cmp_gt_f32_e32 vcc, s78, v0
	v_mov_b32_e32 v113, v225
	v_mov_b32_e32 v112, v225
	v_readfirstlane_b32 s18, v1
	s_not_b32 s63, s18
	s_add_i32 s18, s62, s63
	s_max_i32 s18, s18, 0
	s_lshr_b32 s18, s18, 6
	s_and_b64 s[64:65], vcc, exec
	s_cselect_b32 s64, s18, 0
	s_add_i32 s84, s62, s75
	s_lshl_b64 s[66:67], s[8:9], 2
	s_add_u32 s86, s73, s66
	s_addc_u32 s87, s74, s67
	s_ashr_i32 s9, s84, 31
	s_add_u32 s82, s84, s76
	s_addc_u32 s83, s9, 0
	s_lshl_b32 s18, s8, 7
	s_lshl_b32 s8, s8, 8
	s_lshl_b32 s65, s64, 18
	s_add_i32 s8, s65, s8
	v_add_u32_e32 v0, s18, v231
	v_add_u32_e32 v210, s8, v232
	s_lshl_b32 s66, s64, 7
	v_lshl_or_b32 v2, v0, 13, v218
	v_lshl_add_u64 v[0:1], s[38:39], 0, v[210:211]
	v_or_b32_e32 v32, s82, v214
	v_mov_b32_e32 v33, s83
	global_load_dwordx4 v[160:163], v210, s[38:39]
	v_add_u32_e32 v210, s66, v2
	v_add_co_u32_e64 v0, s[8:9], s79, v0
	v_lshlrev_b64 v[32:33], 12, v[32:33]
	s_nop 0
	v_addc_co_u32_e64 v1, s[8:9], 0, v1, s[8:9]
	v_lshl_add_u64 v[2:3], s[36:37], 0, v[210:211]
	v_lshl_add_u64 v[32:33], s[34:35], 0, v[32:33]
	global_load_dword v34, v211, s[86:87]
	global_load_dwordx4 v[164:167], v210, s[36:37]
	global_load_dwordx4 v[168:171], v[0:1], off
	v_add_co_u32_e64 v0, s[8:9], s80, v2
	v_lshl_add_u64 v[32:33], s[18:19], 1, v[32:33]
	s_nop 0
	v_addc_co_u32_e64 v1, s[8:9], 0, v3, s[8:9]
	v_lshl_add_u64 v[32:33], v[32:33], 0, v[222:223]
	global_load_dwordx4 v[172:175], v[0:1], off
	global_load_dwordx4 v[176:179], v[32:33], off
	global_load_dwordx4 v[180:183], v[32:33], off offset:32
	global_load_dwordx4 v[184:187], v[32:33], off offset:64
	global_load_dwordx4 v[188:191], v[32:33], off offset:96
	global_load_dwordx4 v[192:195], v[32:33], off offset:128
	global_load_dwordx4 v[196:199], v[32:33], off offset:160
	global_load_dwordx4 v[200:203], v[32:33], off offset:192
	global_load_dwordx4 v[204:207], v[32:33], off offset:224
	s_lshl_b32 s85, s11, 2
	s_add_i32 s85, s85, 4
	s_bitcmp1_b32 s64, 0
	s_cselect_b32 s8, 0x4400, 0
	s_add_i32 s8, s8, 0
	v_add_u32_e32 v33, s8, v220
	v_add_u32_e32 v32, s8, v216
	v_add_u32_e32 v35, 0x8800, v33
	v_add_u32_e32 v33, 0xaa00, v33
	v_mov_b32_e32 v3, v225
	v_mov_b32_e32 v2, v225
	v_mov_b32_e32 v1, v225
	v_mov_b32_e32 v0, v225
	v_mov_b32_e32 v111, v225
	v_mov_b32_e32 v110, v225
	v_mov_b32_e32 v109, v225
	v_mov_b32_e32 v108, v225
	v_mov_b32_e32 v107, v225
	v_mov_b32_e32 v106, v225
	v_mov_b32_e32 v105, v225
	v_mov_b32_e32 v104, v225
	v_mov_b32_e32 v103, v225
	v_mov_b32_e32 v102, v225
	v_mov_b32_e32 v101, v225
	v_mov_b32_e32 v100, v225
	v_mov_b32_e32 v99, v225
	v_mov_b32_e32 v98, v225
	v_mov_b32_e32 v97, v225
	v_mov_b32_e32 v96, v225
	v_mov_b32_e32 v95, v225
	v_mov_b32_e32 v94, v225
	v_mov_b32_e32 v93, v225
	v_mov_b32_e32 v92, v225
	v_mov_b32_e32 v91, v225
	s_cmp_ge_i32 s64, s85
	v_mov_b32_e32 v90, v225
	v_mov_b32_e32 v89, v225
	v_mov_b32_e32 v88, v225
	v_mov_b32_e32 v87, v225
	v_mov_b32_e32 v86, v225
	v_mov_b32_e32 v85, v225
	v_mov_b32_e32 v84, v225
	v_mov_b32_e32 v83, v225
	v_mov_b32_e32 v82, v225
	v_mov_b32_e32 v81, v225
	v_mov_b32_e32 v80, v225
	v_mov_b32_e32 v47, v225
	v_mov_b32_e32 v46, v225
	v_mov_b32_e32 v45, v225
	v_mov_b32_e32 v44, v225
	s_waitcnt vmcnt(12)
	ds_write_b128 v32, v[160:163]
	s_waitcnt vmcnt(9)
	ds_write_b128 v32, v[168:171] offset:8704
	ds_write2_b64 v35, v[164:165], v[166:167] offset1:1
	s_waitcnt vmcnt(8)
	ds_write2_b64 v33, v[172:173], v[174:175] offset1:1
	v_readfirstlane_b32 s86, v34
	v_mov_b32_e32 v43, v225
	v_mov_b32_e32 v42, v225
	v_mov_b32_e32 v41, v225
	v_mov_b32_e32 v40, v225
	v_mov_b32_e32 v39, v225
	v_mov_b32_e32 v38, v225
	v_mov_b32_e32 v37, v225
	v_mov_b32_e32 v36, v225
	v_mov_b32_e32 v35, v225
	v_mov_b32_e32 v34, v225
	v_mov_b32_e32 v33, v225
	v_mov_b32_e32 v32, v225
	s_waitcnt lgkmcnt(0)
	s_barrier
; #define LAS __attribute__((address_space(3)))
; #define AT_LOADK(tt) do { const unsigned ko = kgo + (unsigned)(tt) * (64 * BR * 2); ks0 = *(const u32x4*)((const char*)K + ko); ks1 = *(const u32x4*)((const char*)K + ko + 32 * BR * 2); } while (0)
; #define AT_LOADV(tt) do { const unsigned vo = vgo + (unsigned)(tt) * 128; vs0 = *(const u32x4*)((const char*)Vt + vo); vs1 = *(const u32x4*)((const char*)Vt + vo + 64 * SEQ * 2); } while (0)
; #define AT_WRITEK(buf) do { *(LAS u32x4*)(lds + (buf) * KT_BYTES + kl) = ks0; *(LAS u32x4*)(lds + (buf) * KT_BYTES + kl + 32 * KROW) = ks1; } while (0)
; #define AT_WRITEV(buf) do { \
;         *(LAS u32x2*)(lds + (buf) * VT_BYTES + vl) = (u32x2){vs0.x, vs0.y}; *(LAS u32x2*)(lds + (buf) * VT_BYTES + vl + 8) = (u32x2){vs0.z, vs0.w}; \
;         *(LAS u32x2*)(lds + (buf) * VT_BYTES + vl + 64 * VROW) = (u32x2){vs1.x, vs1.y}; *(LAS u32x2*)(lds + (buf) * VT_BYTES + vl + 64 * VROW + 8) = (u32x2){vs1.z, vs1.w}; } while (0)
; __device__ __forceinline__ void attn_unit(int b, int h, int qb, bf16_t* Q, const bf16_t* __restrict__ K, const bf16_t* __restrict__ Vt, const bf16_t* __restrict__ Z, const float* __restrict__ hg, float lam, ...
;     ...
;     const int NT = 4 * (qb + 1), last_w = (qw0 + 31) >> 6;
;     int tlo_w = 0; if (Dwin < 4096.f) { const int kmin_w = qw0 - (int)Dwin - 1; tlo_w = kmin_w > 0 ? (kmin_w >> 6) : 0; }
;     f32x16 o[2][4];
; #pragma unroll
;     for (int s = 0; s < 2; ++s)
; #pragma unroll
;         for (int d = 0; d < 4; ++d)
; #pragma unroll
;             for (int r = 0; r < 16; ++r) o[s][d][r] = 0.f;
;     float lsum[2] = {0.f, 0.f};
;     u32x4 ks0, ks1, vs0, vs1;
;     ...
;     AT_LOADK(tfirst); AT_LOADV(tfirst); AT_WRITEK(tfirst & 1); AT_WRITEV(tfirst & 1);
;     __syncthreads();
;     for (int t = tfirst; t < NT; ++t) {
;         const int cur = t & 1; const bool more = (t + 1 < NT), active = (t <= last_w) && (t >= tlo_w), band = (64 * t + 63 > qw0);
;         const LAS unsigned char* kb = lds + cur * KT_BYTES + r32 * KROW + hi * 16;
;         const LAS unsigned char* vb = lds + AT_VOFF + cur * VT_BYTES + r32 * VROW + hi * 8;
;         if (more) AT_LOADK(t + 1);
	s_cbranch_scc1 .LBB0_236
	s_add_i32 s8, s84, s63
	s_max_i32 s8, s8, 0
	s_ashr_i32 s87, s84, 6
	s_lshr_b32 s11, s8, 6
	s_and_b64 s[8:9], vcc, exec
	s_cselect_b32 s88, s11, 0
	v_add_u32_e32 v0, s62, v239
	s_lshl_b32 s89, s64, 6
	v_subrev_u32_e32 v223, s89, v0
	v_add_u32_e32 v0, s62, v238
	v_sub_u32_e32 v246, v237, v0
	v_add_u32_e32 v0, s66, v240
	s_lshl_b32 s8, s10, 20
	v_subrev_u32_e32 v226, s8, v0
	v_add_u32_e32 v0, s65, v241
	s_lshl_b32 s8, s10, 8
	v_mov_b32_e32 v32, v211
	v_mov_b32_e32 v33, v211
	v_mov_b32_e32 v46, v211
	v_mov_b32_e32 v47, v211
	v_subrev_u32_e32 v210, s8, v0
	v_mov_b32_e32 v34, v211
	v_mov_b32_e32 v35, v211
	v_mov_b32_e32 v36, v211
	v_mov_b32_e32 v37, v211
	v_mov_b32_e32 v38, v211
	v_mov_b32_e32 v39, v211
	v_mov_b32_e32 v40, v211
	v_mov_b32_e32 v41, v211
	v_mov_b32_e32 v42, v211
	v_mov_b32_e32 v43, v211
	v_mov_b32_e32 v44, v211
	v_mov_b32_e32 v45, v211
	v_mov_b32_e32 v224, 0
	v_mov_b64_e32 v[94:95], v[46:47]
	v_mov_b64_e32 v[110:111], v[46:47]
	v_mov_b64_e32 v[126:127], v[46:47]
	v_mov_b64_e32 v[0:1], v[32:33]
	v_mov_b64_e32 v[16:17], v[32:33]
	v_mov_b64_e32 v[62:63], v[46:47]
	v_mov_b64_e32 v[78:79], v[46:47]
	v_mov_b64_e32 v[92:93], v[44:45]
	v_mov_b64_e32 v[90:91], v[42:43]
	v_mov_b64_e32 v[88:89], v[40:41]
	v_mov_b64_e32 v[86:87], v[38:39]
	v_mov_b64_e32 v[84:85], v[36:37]
	v_mov_b64_e32 v[82:83], v[34:35]
	v_mov_b64_e32 v[80:81], v[32:33]
	v_mov_b64_e32 v[108:109], v[44:45]
	v_mov_b64_e32 v[106:107], v[42:43]
	v_mov_b64_e32 v[104:105], v[40:41]
	v_mov_b64_e32 v[102:103], v[38:39]
	v_mov_b64_e32 v[100:101], v[36:37]
	v_mov_b64_e32 v[98:99], v[34:35]
	v_mov_b64_e32 v[96:97], v[32:33]
	v_mov_b64_e32 v[124:125], v[44:45]
	v_mov_b64_e32 v[122:123], v[42:43]
	v_mov_b64_e32 v[120:121], v[40:41]
	v_mov_b64_e32 v[118:119], v[38:39]
	v_mov_b64_e32 v[116:117], v[36:37]
	v_mov_b64_e32 v[114:115], v[34:35]
	v_mov_b64_e32 v[112:113], v[32:33]
	v_mov_b64_e32 v[2:3], v[34:35]
	v_mov_b64_e32 v[4:5], v[36:37]
	v_mov_b64_e32 v[6:7], v[38:39]
	v_mov_b64_e32 v[8:9], v[40:41]
	v_mov_b64_e32 v[10:11], v[42:43]
	v_mov_b64_e32 v[12:13], v[44:45]
	v_mov_b64_e32 v[14:15], v[46:47]
	v_mov_b64_e32 v[18:19], v[34:35]
	v_mov_b64_e32 v[20:21], v[36:37]
	v_mov_b64_e32 v[22:23], v[38:39]
	v_mov_b64_e32 v[24:25], v[40:41]
	v_mov_b64_e32 v[26:27], v[42:43]
	v_mov_b64_e32 v[28:29], v[44:45]
	v_mov_b64_e32 v[30:31], v[46:47]
	v_mov_b64_e32 v[60:61], v[44:45]
	v_mov_b64_e32 v[58:59], v[42:43]
	v_mov_b64_e32 v[56:57], v[40:41]
	v_mov_b64_e32 v[54:55], v[38:39]
	v_mov_b64_e32 v[52:53], v[36:37]
	v_mov_b64_e32 v[50:51], v[34:35]
	v_mov_b64_e32 v[48:49], v[32:33]
	v_mov_b64_e32 v[76:77], v[44:45]
	v_mov_b64_e32 v[74:75], v[42:43]
	v_mov_b64_e32 v[72:73], v[40:41]
	v_mov_b64_e32 v[70:71], v[38:39]
	v_mov_b64_e32 v[68:69], v[36:37]
	v_mov_b64_e32 v[66:67], v[34:35]
	v_mov_b64_e32 v[64:65], v[32:33]
	v_mov_b32_e32 v225, v224
	global_load_dwordx4 v[160:163], v210, s[38:39]
	v_add_u32_e32 v128, 0x20000, v210
	global_load_dwordx4 v[168:171], v128, s[38:39]
	global_load_dwordx4 v[164:167], v226, s[36:37]
	v_add_u32_e32 v128, 0x80000, v226
	global_load_dwordx4 v[172:175], v128, s[36:37]
	.p2align 6

; template <class Epi, class Sched, bool ALIGN_EPI = false, bool SP2 = false>
; __device__ __forceinline__ void gemm_phase(PG8_LAS unsigned char* lds, const Gemm g, const Sched& S, const Epi& E, int tid_in) {
;     ...
;         const bool has_next = S.next(ui + 1, nxt);
;         const char* nA = has_next ? (const char*)g.A + (size_t)nxt.pm * tstep : cA; const char* nB = has_next ? (const char*)g.Bt + (size_t)nxt.pn * tstep : cB;
;         for (int t = 0; t < nt; t += 2) {
;             const bool last = (t == nt - 2);
;             const char* a1 = cA + (size_t)(t + 1) * kstep;
;             const char* a2 = last ? nA : cA + (size_t)(t + 2) * kstep; const char* b2 = last ? nB : cB + (size_t)(t + 2) * kstep;
;             const char* a3 = a2 + kstep; const char* b3 = b2 + kstep;
;     ...
; #pragma unroll
;         for (int a = 0; a < 2; ++a)
; #pragma unroll
;             for (int b = 0; b < 2; ++b)
; #pragma unroll
;                 for (int m = 0; m < 4; ++m)
; #pragma unroll
;                     for (int n = 0; n < 2; ++n) acc[a][b][m][n] = (f32x4){0.f, 0.f, 0.f, 0.f};
.LBB0_301:
	s_ashr_i32 s43, s42, 31
	s_lshl_b64 s[52:53], s[42:43], 20
	s_add_u32 s52, s34, s52
	s_addc_u32 s53, s35, s53
	s_and_b64 s[54:55], s[10:11], exec
	s_cselect_b32 s43, s53, s61
	s_cselect_b32 s57, s52, s60
	s_ashr_i32 s41, s40, 31
	s_lshl_b64 s[54:55], s[40:41], 20
	s_add_u32 s54, s66, s54
	s_addc_u32 s55, s67, s55
	s_and_b64 s[64:65], s[10:11], exec
	s_cselect_b32 s41, s55, s63
	s_cselect_b32 s82, s54, s62
	s_add_u32 s60, s60, 0x80080
	s_addc_u32 s61, s61, 0
	s_add_u32 s83, s62, 0x100
	v_mov_b32_e32 v0, 0
	s_addc_u32 s84, s63, 0
	s_mov_b32 s85, -2
	s_waitcnt lgkmcnt(0)
	v_mov_b32_e32 v1, v0
	v_mov_b32_e32 v2, v0
	v_mov_b32_e32 v3, v0
	v_mov_b32_e32 v4, v0
	v_mov_b32_e32 v5, v0
	v_mov_b32_e32 v6, v0
	v_mov_b32_e32 v7, v0
	v_mov_b32_e32 v16, v0
	v_mov_b32_e32 v17, v0
	v_mov_b32_e32 v18, v0
	v_mov_b32_e32 v19, v0
	v_mov_b32_e32 v20, v0
	v_mov_b32_e32 v21, v0
	v_mov_b32_e32 v22, v0
	v_mov_b32_e32 v23, v0
	v_mov_b32_e32 v32, v0
	v_mov_b32_e32 v33, v0
	v_mov_b32_e32 v34, v0
	v_mov_b32_e32 v35, v0
	v_mov_b32_e32 v36, v0
	v_mov_b32_e32 v37, v0
	v_mov_b32_e32 v38, v0
	v_mov_b32_e32 v39, v0
	v_mov_b32_e32 v48, v0
	v_mov_b32_e32 v49, v0
	v_mov_b32_e32 v50, v0
	v_mov_b32_e32 v51, v0
	v_mov_b32_e32 v52, v0
	v_mov_b32_e32 v53, v0
	v_mov_b32_e32 v54, v0
	v_mov_b32_e32 v55, v0
	v_mov_b32_e32 v8, v0
	v_mov_b32_e32 v9, v0
	v_mov_b32_e32 v10, v0
	v_mov_b32_e32 v11, v0
	v_mov_b32_e32 v12, v0
	v_mov_b32_e32 v13, v0
	v_mov_b32_e32 v14, v0
	v_mov_b32_e32 v15, v0
	v_mov_b32_e32 v24, v0
	v_mov_b32_e32 v25, v0
	v_mov_b32_e32 v26, v0
	v_mov_b32_e32 v27, v0
	v_mov_b32_e32 v28, v0
	v_mov_b32_e32 v29, v0
	v_mov_b32_e32 v30, v0
	v_mov_b32_e32 v31, v0
	v_mov_b32_e32 v40, v0
	v_mov_b32_e32 v41, v0
	v_mov_b32_e32 v42, v0
	v_mov_b32_e32 v43, v0
	v_mov_b32_e32 v44, v0
	v_mov_b32_e32 v45, v0
	v_mov_b32_e32 v46, v0
	v_mov_b32_e32 v47, v0
	v_mov_b32_e32 v56, v0
	v_mov_b32_e32 v57, v0
	v_mov_b32_e32 v58, v0
	v_mov_b32_e32 v59, v0
	v_mov_b32_e32 v60, v0
	v_mov_b32_e32 v61, v0
	v_mov_b32_e32 v62, v0
	v_mov_b32_e32 v63, v0
	v_mov_b32_e32 v64, v0
	v_mov_b32_e32 v65, v0
	v_mov_b32_e32 v66, v0
	v_mov_b32_e32 v67, v0
	v_mov_b32_e32 v68, v0
	v_mov_b32_e32 v69, v0
	v_mov_b32_e32 v70, v0
	v_mov_b32_e32 v71, v0
	v_mov_b32_e32 v80, v0
	v_mov_b32_e32 v81, v0
	v_mov_b32_e32 v82, v0
	v_mov_b32_e32 v83, v0
	v_mov_b32_e32 v84, v0
	v_mov_b32_e32 v85, v0
	v_mov_b32_e32 v86, v0
	v_mov_b32_e32 v87, v0
	v_mov_b32_e32 v96, v0
	v_mov_b32_e32 v97, v0
	v_mov_b32_e32 v98, v0
	v_mov_b32_e32 v99, v0
	v_mov_b32_e32 v100, v0
	v_mov_b32_e32 v101, v0
	v_mov_b32_e32 v102, v0
	v_mov_b32_e32 v103, v0
	v_mov_b32_e32 v112, v0
	v_mov_b32_e32 v113, v0
	v_mov_b32_e32 v114, v0
	v_mov_b32_e32 v115, v0
	v_mov_b32_e32 v116, v0
	v_mov_b32_e32 v117, v0
	v_mov_b32_e32 v118, v0
	v_mov_b32_e32 v119, v0
	v_mov_b32_e32 v72, v0
	v_mov_b32_e32 v73, v0
	v_mov_b32_e32 v74, v0
	v_mov_b32_e32 v75, v0
	v_mov_b32_e32 v76, v0
	v_mov_b32_e32 v77, v0
	v_mov_b32_e32 v78, v0
	v_mov_b32_e32 v79, v0
	v_mov_b32_e32 v88, v0
	v_mov_b32_e32 v89, v0
	v_mov_b32_e32 v90, v0
	v_mov_b32_e32 v91, v0
	v_mov_b32_e32 v92, v0
	v_mov_b32_e32 v93, v0
	v_mov_b32_e32 v94, v0
	v_mov_b32_e32 v95, v0
	v_mov_b32_e32 v104, v0
	v_mov_b32_e32 v105, v0
	v_mov_b32_e32 v106, v0
	v_mov_b32_e32 v107, v0
	v_mov_b32_e32 v108, v0
	v_mov_b32_e32 v109, v0
	v_mov_b32_e32 v110, v0
	v_mov_b32_e32 v111, v0
	v_mov_b32_e32 v120, v0
	v_mov_b32_e32 v121, v0
	v_mov_b32_e32 v122, v0
	v_mov_b32_e32 v123, v0
	v_mov_b32_e32 v124, v0
	v_mov_b32_e32 v125, v0
	v_mov_b32_e32 v126, v0
	v_mov_b32_e32 v127, v0
	s_waitcnt vmcnt(0)
	.p2align 6

; template <class Epi, class Sched, bool ALIGN_EPI = false, bool SP2 = false>
; __device__ __forceinline__ void gemm_phase(PG8_LAS unsigned char* lds, const Gemm g, const Sched& S, const Epi& E, int tid_in) {
;     ...
;         const bool has_next = S.next(ui + 1, nxt);
;         const char* nA = has_next ? (const char*)g.A + (size_t)nxt.pm * tstep : cA; const char* nB = has_next ? (const char*)g.Bt + (size_t)nxt.pn * tstep : cB;
;         for (int t = 0; t < nt; t += 2) {
;             const bool last = (t == nt - 2);
;             const char* a1 = cA + (size_t)(t + 1) * kstep;
;             const char* a2 = last ? nA : cA + (size_t)(t + 2) * kstep; const char* b2 = last ? nB : cB + (size_t)(t + 2) * kstep;
;             const char* a3 = a2 + kstep; const char* b3 = b2 + kstep;
;     ...
; #pragma unroll
;         for (int a = 0; a < 2; ++a)
; #pragma unroll
;             for (int b = 0; b < 2; ++b)
; #pragma unroll
;                 for (int m = 0; m < 4; ++m)
; #pragma unroll
;                     for (int n = 0; n < 2; ++n) acc[a][b][m][n] = (f32x4){0.f, 0.f, 0.f, 0.f};
.LBB0_351:
	s_ashr_i32 s57, s56, 31
	s_lshl_b64 s[58:59], s[56:57], 19
	s_add_u32 s58, s26, s58
	s_addc_u32 s59, s27, s59
	s_and_b64 s[60:61], s[4:5], exec
	s_cselect_b32 s9, s59, s63
	s_cselect_b32 s11, s58, s62
	s_ashr_i32 s55, s54, 31
	s_lshl_b64 s[60:61], s[54:55], 19
	s_add_u32 s60, s71, s60
	s_addc_u32 s61, s72, s61
	s_and_b64 s[66:67], s[4:5], exec
	s_cselect_b32 s55, s61, s65
	s_cselect_b32 s57, s60, s64
	s_add_u32 s62, s62, 0x40080
	s_addc_u32 s63, s63, 0
	s_add_u32 s90, s64, 0x100
	v_mov_b32_e32 v0, 0
	s_addc_u32 s91, s65, 0
	s_mov_b32 s92, -2
	v_mov_b32_e32 v1, v0
	v_mov_b32_e32 v2, v0
	v_mov_b32_e32 v3, v0
	v_mov_b32_e32 v4, v0
	v_mov_b32_e32 v5, v0
	v_mov_b32_e32 v6, v0
	v_mov_b32_e32 v7, v0
	v_mov_b32_e32 v16, v0
	v_mov_b32_e32 v17, v0
	v_mov_b32_e32 v18, v0
	v_mov_b32_e32 v19, v0
	v_mov_b32_e32 v20, v0
	v_mov_b32_e32 v21, v0
	v_mov_b32_e32 v22, v0
	v_mov_b32_e32 v23, v0
	v_mov_b32_e32 v32, v0
	v_mov_b32_e32 v33, v0
	v_mov_b32_e32 v34, v0
	v_mov_b32_e32 v35, v0
	v_mov_b32_e32 v36, v0
	v_mov_b32_e32 v37, v0
	v_mov_b32_e32 v38, v0
	v_mov_b32_e32 v39, v0
	v_mov_b32_e32 v48, v0
	v_mov_b32_e32 v49, v0
	v_mov_b32_e32 v50, v0
	v_mov_b32_e32 v51, v0
	v_mov_b32_e32 v52, v0
	v_mov_b32_e32 v53, v0
	v_mov_b32_e32 v54, v0
	v_mov_b32_e32 v55, v0
	v_mov_b32_e32 v8, v0
	v_mov_b32_e32 v9, v0
	v_mov_b32_e32 v10, v0
	v_mov_b32_e32 v11, v0
	v_mov_b32_e32 v12, v0
	v_mov_b32_e32 v13, v0
	v_mov_b32_e32 v14, v0
	v_mov_b32_e32 v15, v0
	v_mov_b32_e32 v24, v0
	v_mov_b32_e32 v25, v0
	v_mov_b32_e32 v26, v0
	v_mov_b32_e32 v27, v0
	v_mov_b32_e32 v28, v0
	v_mov_b32_e32 v29, v0
	v_mov_b32_e32 v30, v0
	v_mov_b32_e32 v31, v0
	v_mov_b32_e32 v40, v0
	v_mov_b32_e32 v41, v0
	v_mov_b32_e32 v42, v0
	v_mov_b32_e32 v43, v0
	v_mov_b32_e32 v44, v0
	v_mov_b32_e32 v45, v0
	v_mov_b32_e32 v46, v0
	v_mov_b32_e32 v47, v0
	v_mov_b32_e32 v56, v0
	v_mov_b32_e32 v57, v0
	v_mov_b32_e32 v58, v0
	v_mov_b32_e32 v59, v0
	v_mov_b32_e32 v60, v0
	v_mov_b32_e32 v61, v0
	v_mov_b32_e32 v62, v0
	v_mov_b32_e32 v63, v0
	v_mov_b32_e32 v64, v0
	v_mov_b32_e32 v65, v0
	v_mov_b32_e32 v66, v0
	v_mov_b32_e32 v67, v0
	v_mov_b32_e32 v68, v0
	v_mov_b32_e32 v69, v0
	v_mov_b32_e32 v70, v0
	v_mov_b32_e32 v71, v0
	v_mov_b32_e32 v80, v0
	v_mov_b32_e32 v81, v0
	v_mov_b32_e32 v82, v0
	v_mov_b32_e32 v83, v0
	v_mov_b32_e32 v84, v0
	v_mov_b32_e32 v85, v0
	v_mov_b32_e32 v86, v0
	v_mov_b32_e32 v87, v0
	v_mov_b32_e32 v96, v0
	v_mov_b32_e32 v97, v0
	v_mov_b32_e32 v98, v0
	v_mov_b32_e32 v99, v0
	v_mov_b32_e32 v100, v0
	v_mov_b32_e32 v101, v0
	v_mov_b32_e32 v102, v0
	v_mov_b32_e32 v103, v0
	v_mov_b32_e32 v112, v0
	v_mov_b32_e32 v113, v0
	v_mov_b32_e32 v114, v0
	v_mov_b32_e32 v115, v0
	v_mov_b32_e32 v116, v0
	v_mov_b32_e32 v117, v0
	v_mov_b32_e32 v118, v0
	v_mov_b32_e32 v119, v0
	v_mov_b32_e32 v72, v0
	v_mov_b32_e32 v73, v0
	v_mov_b32_e32 v74, v0
	v_mov_b32_e32 v75, v0
	v_mov_b32_e32 v76, v0
	v_mov_b32_e32 v77, v0
	v_mov_b32_e32 v78, v0
	v_mov_b32_e32 v79, v0
	v_mov_b32_e32 v88, v0
	v_mov_b32_e32 v89, v0
	v_mov_b32_e32 v90, v0
	v_mov_b32_e32 v91, v0
	v_mov_b32_e32 v92, v0
	v_mov_b32_e32 v93, v0
	v_mov_b32_e32 v94, v0
	v_mov_b32_e32 v95, v0
	v_mov_b32_e32 v104, v0
	v_mov_b32_e32 v105, v0
	v_mov_b32_e32 v106, v0
	v_mov_b32_e32 v107, v0
	v_mov_b32_e32 v108, v0
	v_mov_b32_e32 v109, v0
	v_mov_b32_e32 v110, v0
	v_mov_b32_e32 v111, v0
	v_mov_b32_e32 v120, v0
	v_mov_b32_e32 v121, v0
	v_mov_b32_e32 v122, v0
	v_mov_b32_e32 v123, v0
	v_mov_b32_e32 v124, v0
	v_mov_b32_e32 v125, v0
	v_mov_b32_e32 v126, v0
	v_mov_b32_e32 v127, v0
	s_waitcnt vmcnt(0)
	.p2align 6

; template <bool FULL>
; __device__ __forceinline__ void s5_pass(const Params& P, LAS unsigned char* lds, int bx, int tid_in) {
;     ...
;         const int g = task & 127, bp = (task >> 7) & 3, seg = task >> 9;
;         if (!FULL && seg == 7) continue;
;         const float ar0 = AB[(g * 64 + r32) * 2], ai0 = AB[(g * 64 + r32) * 2 + 1], ar1 = AB[(g * 64 + 32 + r32) * 2], ai1 = AB[(g * 64 + 32 + r32) * 2 + 1];
;         bf16x8 bfr[4], cfr[4];
; #pragma unroll
;         for (int j = 0; j < 4; ++j) { bfr[j] = *(const bf16x8*)(BBT + ((g * 4 + j) * 32 + r32) * 16 + 8 * hi); if (FULL) cfr[j] = *(const bf16x8*)(CMT + (g * 16 + l16) * 128 + 32 * j + 8 * kg); }
;         bf16x8 dh, dl;
;         if (FULL) { const float d = P.in[20][g * 16 + l16]; const unsigned h16 = f2bf(d); const unsigned l16b = f2bf(d - __builtin_bit_cast(float, h16 << 16));
; #pragma unroll
;           for (int i = 0; i < 8; ++i) { const bool on = (kg < 2) && (8 * kg + i == l16); dh[i] = on ? (short)h16 : (short)0; dl[i] = on ? (short)l16b : (short)0; } }
;         const int m = r32, bsel = (m >> 2) & 1, tok = (m & 3) + 4 * (m >> 3);
;         const int tbeg = seg * S5_SEGLEN;
;         const bf16_t* u32p = U + ((size_t)(bp + 4 * bsel) * SEQ + tbeg + tok) * BR + g * 16 + 8 * hi;
;         const bf16_t* u16p = U + ((size_t)bp * SEQ + tbeg + l16) * BR + g * 16 + 8 * (kg & 1);
;         bf16_t* yp = YG + ((size_t)bp * SEQ + tbeg + 4 * kg) * BR + g * 16 + l16;
;         float h0r = 0.f, h0i = 0.f, h1r = 0.f, h1i = 0.f;
;         if (FULL && seg > 0) {
;             float p0r = ar0, p0i = ai0, p1r = ar1, p1i = ai1;
; #pragma unroll
;             for (int q = 0; q < 9; ++q) { const float a = p0r * p0r - p0i * p0i, b2 = 2.f * p0r * p0i, c = p1r * p1r - p1i * p1i, d2 = 2.f * p1r * p1i; p0r = a; p0i = b2; p1r = c; p1i = d2; }
;             for (int j = 0; j < seg; ++j) { const f32x4 e = SEG[(size_t)(task - (seg - j) * 512) * 64 + lane];
;                 const float n0r = p0r * h0r - p0i * h0i + e[0], n0i = p0r * h0i + p0i * h0r + e[1], n1r = p1r * h1r - p1i * h1i + e[2], n1i = p1r * h1i + p1i * h1r + e[3];
;                 h0r = n0r; h0i = n0i; h1r = n1r; h1i = n1i; }
;         }
;         bf16x8 ua = *(const bf16x8*)u32p, ub0, ub1;
;         if (FULL) { ub0 = *(const bf16x8*)u16p; ub1 = *(const bf16x8*)(u16p + (size_t)4 * SEQ * BR); }
.LBB0_403:
	s_and_b32 s12, s4, 0xfffffe00
	s_cmpk_eq_i32 s12, 0xe00
	s_cbranch_scc1 .LBB0_402
	s_ashr_i32 s13, s12, 31
	s_bfe_u32 s5, s4, 0x20007
	v_mov_b32_e32 v1, s13
	v_or_b32_e32 v0, s12, v88
	v_lshl_add_u32 v84, s5, 12, v106
	s_and_b32 s8, s4, 0x7f
	v_lshl_add_u64 v[0:1], v[0:1], 0, v[84:85]
	v_lshl_or_b32 v2, s8, 9, v107
	v_lshl_or_b32 v84, s8, 12, v108
	v_or_b32_e32 v4, s5, v89
	global_load_dwordx2 v[96:97], v2, s[46:47]
	global_load_dwordx2 v[98:99], v2, s[46:47] offset:256
	v_lshl_add_u64 v[2:3], v[86:87], 0, v[84:85]
	v_lshlrev_b32_e32 v84, 12, v4
	v_lshl_add_u64 v[4:5], v[84:85], 0, s[12:13]
	v_or_b32_e32 v4, v4, v88
	v_lshlrev_b64 v[4:5], 12, v[4:5]
	v_lshl_add_u64 v[4:5], s[34:35], 0, v[4:5]
	s_lshl_b32 s8, s8, 5
	v_lshl_add_u64 v[4:5], v[4:5], 0, s[8:9]
	v_mov_b32_e32 v95, v85
	v_lshl_add_u64 v[4:5], v[4:5], 0, v[94:95]
	v_lshlrev_b64 v[0:1], 12, v[0:1]
	s_and_b32 s5, s18, 0x7f
	v_lshl_or_b32 v0, s5, 5, v0
	v_mov_b32_e32 v34, 0
	v_lshl_add_u64 v[100:101], v[92:93], 0, v[0:1]
	global_load_dwordx4 v[64:67], v[2:3], off
	global_load_dwordx4 v[68:71], v[2:3], off offset:1024
	global_load_dwordx4 v[72:75], v[2:3], off offset:2048
	global_load_dwordx4 v[76:79], v[2:3], off offset:3072
	v_mov_b32_e32 v116, v4
	v_mov_b32_e32 v117, v5
	s_add_i32 m0, s50, 0
	s_nop 0
	global_load_lds_dwordx4 v[116:117], off
	v_lshl_add_u64 v[116:117], v[116:117], 0, s[10:11]
	s_add_i32 m0, s50, 1024
	s_nop 0
	global_load_lds_dwordx4 v[116:117], off
	v_lshl_add_u64 v[116:117], v[116:117], 0, s[10:11]
	s_add_i32 m0, s50, 2048
	s_nop 0
	global_load_lds_dwordx4 v[116:117], off
	v_lshl_add_u64 v[116:117], v[116:117], 0, s[10:11]
	s_add_i32 m0, s50, 3072
	s_nop 0
	global_load_lds_dwordx4 v[116:117], off
	v_lshl_add_u64 v[116:117], v[116:117], 0, s[10:11]
	s_add_i32 m0, s50, 4096
	s_nop 0
	global_load_lds_dwordx4 v[116:117], off
	v_lshl_add_u64 v[116:117], v[116:117], 0, s[10:11]
	s_add_i32 m0, s50, 5120
	s_nop 0
	global_load_lds_dwordx4 v[116:117], off
	v_lshl_add_u64 v[116:117], v[116:117], 0, s[10:11]
	s_add_i32 m0, s50, 6144
	s_nop 0
	global_load_lds_dwordx4 v[116:117], off
	v_lshl_add_u64 v[116:117], v[116:117], 0, s[10:11]
	s_add_i32 m0, s50, 7168
	s_nop 0
	global_load_lds_dwordx4 v[116:117], off
	v_lshl_add_u64 v[116:117], v[116:117], 0, s[10:11]
	s_add_i32 s51, s50, 1024
	v_add_u32_e32 v115, s50, v114
	v_mov_b32_e32 v130, 0
	v_mov_b32_e32 v131, 0
	v_mov_b32_e32 v132, 0
	v_mov_b32_e32 v133, 0
	s_movk_i32 s56, 32
	s_waitcnt vmcnt(0)
	ds_read_b128 v[120:123], v115
	v_xor_b32_e32 v126, 0x80000000, v97
	v_xor_b32_e32 v129, 0x80000000, v99
	s_mov_b32 m0, s50
	s_waitcnt lgkmcnt(0)
	global_load_lds_dwordx4 v[116:117], off
	v_lshl_add_u64 v[116:117], v[116:117], 0, s[10:11]
	s_mov_b32 s53, 9
	.p2align 6

; template <bool FULL>
; __device__ __forceinline__ void s5_pass(const Params& P, LAS unsigned char* lds, int bx, int tid_in) {
;     ...
;         const float ar0 = AB[(g * 64 + r32) * 2], ai0 = AB[(g * 64 + r32) * 2 + 1], ar1 = AB[(g * 64 + 32 + r32) * 2], ai1 = AB[(g * 64 + 32 + r32) * 2 + 1];
;         bf16x8 bfr[4], cfr[4];
; #pragma unroll
;         for (int j = 0; j < 4; ++j) { bfr[j] = *(const bf16x8*)(BBT + ((g * 4 + j) * 32 + r32) * 16 + 8 * hi); if (FULL) cfr[j] = *(const bf16x8*)(CMT + (g * 16 + l16) * 128 + 32 * j + 8 * kg); }
;         bf16x8 dh, dl;
;         if (FULL) { const float d = P.in[20][g * 16 + l16]; const unsigned h16 = f2bf(d); const unsigned l16b = f2bf(d - __builtin_bit_cast(float, h16 << 16));
; #pragma unroll
;           for (int i = 0; i < 8; ++i) { const bool on = (kg < 2) && (8 * kg + i == l16); dh[i] = on ? (short)h16 : (short)0; dl[i] = on ? (short)l16b : (short)0; } }
;         const int m = r32, bsel = (m >> 2) & 1, tok = (m & 3) + 4 * (m >> 3);
;         const int tbeg = seg * S5_SEGLEN;
;         const bf16_t* u32p = U + ((size_t)(bp + 4 * bsel) * SEQ + tbeg + tok) * BR + g * 16 + 8 * hi;
;         const bf16_t* u16p = U + ((size_t)bp * SEQ + tbeg + l16) * BR + g * 16 + 8 * (kg & 1);
;         bf16_t* yp = YG + ((size_t)bp * SEQ + tbeg + 4 * kg) * BR + g * 16 + l16;
;         float h0r = 0.f, h0i = 0.f, h1r = 0.f, h1i = 0.f;
;         if (FULL && seg > 0) {
;             float p0r = ar0, p0i = ai0, p1r = ar1, p1i = ai1;
; #pragma unroll
;             for (int q = 0; q < 9; ++q) { const float a = p0r * p0r - p0i * p0i, b2 = 2.f * p0r * p0i, c = p1r * p1r - p1i * p1i, d2 = 2.f * p1r * p1i; p0r = a; p0i = b2; p1r = c; p1i = d2; }
;             for (int j = 0; j < seg; ++j) { const f32x4 e = SEG[(size_t)(task - (seg - j) * 512) * 64 + lane];
;                 const float n0r = p0r * h0r - p0i * h0i + e[0], n0i = p0r * h0i + p0i * h0r + e[1], n1r = p1r * h1r - p1i * h1i + e[2], n1i = p1r * h1i + p1i * h1r + e[3];
;                 h0r = n0r; h0i = n0i; h1r = n1r; h1i = n1i; }
;         }
;         bf16x8 ua = *(const bf16x8*)u32p, ub0, ub1;
;         if (FULL) { ub0 = *(const bf16x8*)u16p; ub1 = *(const bf16x8*)(u16p + (size_t)4 * SEQ * BR); }
;         for (int t0 = 0; t0 < S5_SEGLEN; t0 += 16) {
;             const bf16x8 ca = ua; bf16x8 cb0, cb1; if (FULL) { cb0 = ub0; cb1 = ub1; }
.LBB0_423:
	s_bfe_u32 s63, s52, 0x20007
	s_and_b32 s50, s52, 0xfffffe00
	s_and_b32 s40, s33, 0x7f
	s_ashr_i32 s51, s50, 31
	s_lshl_b32 s64, s63, 12
	s_lshl_b32 s40, s40, 5
	v_mov_b32_e32 v3, s51
	v_or_b32_e32 v2, s50, v132
	v_add_u32_e32 v126, s64, v172
	v_or_b32_e32 v4, s63, v135
	s_add_u32 s65, s50, s64
	v_lshl_add_u64 v[2:3], v[2:3], 0, v[126:127]
	v_lshlrev_b32_e32 v126, 12, v4
	s_addc_u32 s66, s51, 0
	v_lshl_add_u64 v[4:5], v[126:127], 0, s[50:51]
	v_mov_b32_e32 v1, s66
	v_or_b32_e32 v0, s65, v124
	v_or_b32_e32 v4, v4, v132
	v_lshlrev_b64 v[0:1], 12, v[0:1]
	v_lshlrev_b64 v[4:5], 12, v[4:5]
	v_lshl_add_u64 v[4:5], s[34:35], 0, v[4:5]
	s_lshl_b32 s50, s62, 1
	s_mov_b32 s51, s41
	v_lshl_add_u64 v[6:7], s[34:35], 0, v[0:1]
	v_lshl_add_u64 v[4:5], v[4:5], 0, s[50:51]
	v_mov_b32_e32 v147, v127
	v_lshl_add_u64 v[6:7], v[6:7], 0, s[50:51]
	v_mov_b32_e32 v149, v127
	v_lshl_add_u64 v[4:5], v[4:5], 0, v[146:147]
	v_lshl_add_u64 v[6:7], v[6:7], 0, v[148:149]
	v_lshlrev_b64 v[2:3], 12, v[2:3]
	s_waitcnt vmcnt(0)
	v_bfe_u32 v4, v8, 16, 1
	v_add3_u32 v4, v8, v4, s53
	v_and_b32_e32 v6, 0xffff0000, v4
	v_sub_f32_e32 v6, v8, v6
	v_lshrrev_b32_e32 v5, 16, v4
	v_bfe_u32 v15, v6, 16, 1
	v_or_b32_e32 v4, s65, v134
	v_cndmask_b32_e64 v7, 0, v5, s[8:9]
	v_cndmask_b32_e64 v8, 0, v5, s[10:11]
	v_cndmask_b32_e64 v9, 0, v5, s[12:13]
	v_cndmask_b32_e64 v10, 0, v5, s[14:15]
	v_cndmask_b32_e64 v11, 0, v5, s[16:17]
	v_cndmask_b32_e64 v12, 0, v5, s[18:19]
	v_cndmask_b32_e64 v13, 0, v5, s[20:21]
	v_cndmask_b32_e64 v14, 0, v5, s[22:23]
	v_mov_b32_e32 v5, s66
	v_lshl_add_u64 v[166:167], v[144:145], 0, v[2:3]
	v_add3_u32 v2, v6, v15, s53
	v_lshlrev_b64 v[4:5], 12, v[4:5]
	v_lshl_add_u64 v[170:171], v[142:143], 0, v[0:1]
	v_lshrrev_b32_e32 v0, 16, v2
	v_perm_b32 v96, v8, v7, s55
	v_lshl_add_u64 v[168:169], v[140:141], 0, v[4:5]
	v_cndmask_b32_e64 v1, 0, v0, s[8:9]
	v_cndmask_b32_e64 v2, 0, v0, s[10:11]
	v_cndmask_b32_e64 v3, 0, v0, s[12:13]
	v_cndmask_b32_e64 v4, 0, v0, s[14:15]
	v_cndmask_b32_e64 v5, 0, v0, s[16:17]
	v_cndmask_b32_e64 v6, 0, v0, s[18:19]
	v_cndmask_b32_e64 v7, 0, v0, s[20:21]
	v_cndmask_b32_e64 v0, 0, v0, s[22:23]
	s_mov_b32 s62, 0
	v_perm_b32 v99, v14, v13, s55
	v_perm_b32 v98, v12, v11, s55
	v_perm_b32 v97, v10, v9, s55
	v_perm_b32 v103, v0, v7, s55
	v_perm_b32 v102, v6, v5, s55
	v_perm_b32 v101, v4, v3, s55
	v_perm_b32 v100, v2, v1, s55
	v_mov_b32_e32 v156, v32
	v_mov_b32_e32 v157, v33
	v_mov_b32_e32 v158, v52
	v_mov_b32_e32 v159, v53
	v_xor_b32_e32 v154, 0x80000000, v151
	v_xor_b32_e32 v155, 0x80000000, v153
	v_lshl_add_u64 v[188:189], v[166:167], 0, s[40:41]
	v_lshl_add_u64 v[188:189], v[188:189], 0, s[82:83]
	s_add_i32 m0, s71, 0
	s_nop 0
	global_load_lds_dwordx4 v[188:189], off
	v_lshl_add_u64 v[188:189], v[188:189], 0, s[42:43]
	s_add_i32 m0, s71, 1024
	s_nop 0
	global_load_lds_dwordx4 v[188:189], off
	v_lshl_add_u64 v[188:189], v[188:189], 0, s[42:43]
	s_add_i32 m0, s71, 2048
	s_nop 0
	global_load_lds_dwordx4 v[188:189], off
	v_lshl_add_u64 v[188:189], v[188:189], 0, s[42:43]
	s_add_i32 m0, s71, 3072
	s_nop 0
	global_load_lds_dwordx4 v[188:189], off
	v_lshl_add_u64 v[188:189], v[188:189], 0, s[42:43]
	s_add_i32 m0, s71, 4096
	s_nop 0
	global_load_lds_dwordx4 v[188:189], off
	v_lshl_add_u64 v[188:189], v[188:189], 0, s[42:43]
	s_add_i32 m0, s71, 5120
	s_nop 0
	global_load_lds_dwordx4 v[188:189], off
	v_lshl_add_u64 v[188:189], v[188:189], 0, s[42:43]
	s_add_i32 m0, s71, 6144
	s_nop 0
	global_load_lds_dwordx4 v[188:189], off
	v_lshl_add_u64 v[188:189], v[188:189], 0, s[42:43]
	s_add_i32 m0, s71, 7168
	s_nop 0
	global_load_lds_dwordx4 v[188:189], off
	v_lshl_add_u64 v[188:189], v[188:189], 0, s[42:43]
	s_add_i32 s72, s71, 1024
	v_or_b32_e32 v224, s65, v134
	v_lshlrev_b32_e32 v224, 12, v224
	v_lshl_add_u32 v224, v124, 1, v224
	v_add_u32_e32 v224, s40, v224
	v_add_u32_e32 v225, 0x3000, v224
	v_add_u32_e32 v224, 0x1000, v224
	v_subrev_u32_e32 v225, 2, v225
	v_cndmask_b32_e64 v224, v225, v224, s[84:85]
	s_movk_i32 s75, 32
	v_add_u32_e32 v186, s71, v184
	v_add_u32_e32 v187, s71, v185
	v_cndmask_b32_e64 v187, v187, v214, s[4:5]
	s_waitcnt vmcnt(0)
	ds_read_b128 v[104:107], v186
	ds_read_b128 v[108:111], v187
	ds_read_b128 v[112:115], v187 offset:64
	s_mov_b32 m0, s71
	s_waitcnt lgkmcnt(0)
	global_load_lds_dwordx4 v[188:189], off
	v_lshl_add_u64 v[188:189], v[188:189], 0, s[42:43]
	s_mov_b32 s74, 9
	.p2align 6

; template <class Epi, class Sched, bool ALIGN_EPI = false, bool SP2 = false>
; __device__ __forceinline__ void gemm_phase(PG8_LAS unsigned char* lds, const Gemm g, const Sched& S, const Epi& E, int tid_in) {
;     ...
;         const bool has_next = S.next(ui + 1, nxt);
;         const char* nA = has_next ? (const char*)g.A + (size_t)nxt.pm * tstep : cA; const char* nB = has_next ? (const char*)g.Bt + (size_t)nxt.pn * tstep : cB;
;         for (int t = 0; t < nt; t += 2) {
;             const bool last = (t == nt - 2);
;             const char* a1 = cA + (size_t)(t + 1) * kstep;
;             const char* a2 = last ? nA : cA + (size_t)(t + 2) * kstep; const char* b2 = last ? nB : cB + (size_t)(t + 2) * kstep;
;             const char* a3 = a2 + kstep; const char* b3 = b2 + kstep;
;     ...
; #pragma unroll
;         for (int a = 0; a < 2; ++a)
; #pragma unroll
;             for (int b = 0; b < 2; ++b)
; #pragma unroll
;                 for (int m = 0; m < 4; ++m)
; #pragma unroll
;                     for (int n = 0; n < 2; ++n) acc[a][b][m][n] = (f32x4){0.f, 0.f, 0.f, 0.f};
.LBB0_451:
	s_ashr_i32 s23, s22, 31
	s_lshl_b64 s[40:41], s[22:23], 20
	s_add_u32 s40, s36, s40
	s_addc_u32 s41, s37, s41
	s_and_b64 s[42:43], s[0:1], exec
	s_cselect_b32 s23, s41, s47
	s_cselect_b32 s67, s40, s46
	s_ashr_i32 s21, s20, 31
	s_lshl_b64 s[42:43], s[20:21], 20
	s_add_u32 s42, s54, s42
	s_addc_u32 s43, s55, s43
	s_and_b64 s[52:53], s[0:1], exec
	s_cselect_b32 s21, s43, s51
	s_cselect_b32 s68, s42, s50
	s_add_u32 s46, s46, 0x80080
	s_addc_u32 s47, s47, 0
	s_add_u32 s71, s50, 0x100
	v_mov_b32_e32 v0, 0
	s_addc_u32 s72, s51, 0
	s_mov_b32 s73, -2
	v_mov_b32_e32 v1, v0
	v_mov_b32_e32 v2, v0
	v_mov_b32_e32 v3, v0
	v_mov_b32_e32 v4, v0
	v_mov_b32_e32 v5, v0
	v_mov_b32_e32 v6, v0
	v_mov_b32_e32 v7, v0
	v_mov_b32_e32 v8, v0
	v_mov_b32_e32 v9, v0
	v_mov_b32_e32 v10, v0
	v_mov_b32_e32 v11, v0
	v_mov_b32_e32 v12, v0
	v_mov_b32_e32 v13, v0
	v_mov_b32_e32 v14, v0
	v_mov_b32_e32 v15, v0
	v_mov_b32_e32 v16, v0
	v_mov_b32_e32 v17, v0
	v_mov_b32_e32 v18, v0
	v_mov_b32_e32 v19, v0
	v_mov_b32_e32 v20, v0
	v_mov_b32_e32 v21, v0
	v_mov_b32_e32 v22, v0
	v_mov_b32_e32 v23, v0
	v_mov_b32_e32 v24, v0
	v_mov_b32_e32 v25, v0
	v_mov_b32_e32 v26, v0
	v_mov_b32_e32 v27, v0
	v_mov_b32_e32 v28, v0
	v_mov_b32_e32 v29, v0
	v_mov_b32_e32 v30, v0
	v_mov_b32_e32 v31, v0
	v_mov_b32_e32 v64, v0
	v_mov_b32_e32 v65, v0
	v_mov_b32_e32 v66, v0
	v_mov_b32_e32 v67, v0
	v_mov_b32_e32 v68, v0
	v_mov_b32_e32 v69, v0
	v_mov_b32_e32 v70, v0
	v_mov_b32_e32 v71, v0
	v_mov_b32_e32 v72, v0
	v_mov_b32_e32 v73, v0
	v_mov_b32_e32 v74, v0
	v_mov_b32_e32 v75, v0
	v_mov_b32_e32 v76, v0
	v_mov_b32_e32 v77, v0
	v_mov_b32_e32 v78, v0
	v_mov_b32_e32 v79, v0
	v_mov_b32_e32 v80, v0
	v_mov_b32_e32 v81, v0
	v_mov_b32_e32 v82, v0
	v_mov_b32_e32 v83, v0
	v_mov_b32_e32 v84, v0
	v_mov_b32_e32 v85, v0
	v_mov_b32_e32 v86, v0
	v_mov_b32_e32 v87, v0
	v_mov_b32_e32 v88, v0
	v_mov_b32_e32 v89, v0
	v_mov_b32_e32 v90, v0
	v_mov_b32_e32 v91, v0
	v_mov_b32_e32 v92, v0
	v_mov_b32_e32 v93, v0
	v_mov_b32_e32 v94, v0
	v_mov_b32_e32 v95, v0
	v_mov_b32_e32 v32, v0
	v_mov_b32_e32 v33, v0
	v_mov_b32_e32 v34, v0
	v_mov_b32_e32 v35, v0
	v_mov_b32_e32 v36, v0
	v_mov_b32_e32 v37, v0
	v_mov_b32_e32 v38, v0
	v_mov_b32_e32 v39, v0
	v_mov_b32_e32 v40, v0
	v_mov_b32_e32 v41, v0
	v_mov_b32_e32 v42, v0
	v_mov_b32_e32 v43, v0
	v_mov_b32_e32 v44, v0
	v_mov_b32_e32 v45, v0
	v_mov_b32_e32 v46, v0
	v_mov_b32_e32 v47, v0
	v_mov_b32_e32 v48, v0
	v_mov_b32_e32 v49, v0
	v_mov_b32_e32 v50, v0
	v_mov_b32_e32 v51, v0
	v_mov_b32_e32 v52, v0
	v_mov_b32_e32 v53, v0
	v_mov_b32_e32 v54, v0
	v_mov_b32_e32 v55, v0
	v_mov_b32_e32 v56, v0
	v_mov_b32_e32 v57, v0
	v_mov_b32_e32 v58, v0
	v_mov_b32_e32 v59, v0
	v_mov_b32_e32 v60, v0
	v_mov_b32_e32 v61, v0
	v_mov_b32_e32 v62, v0
	v_mov_b32_e32 v63, v0
	v_mov_b32_e32 v96, v0
	v_mov_b32_e32 v97, v0
	v_mov_b32_e32 v98, v0
	v_mov_b32_e32 v99, v0
	v_mov_b32_e32 v100, v0
	v_mov_b32_e32 v101, v0
	v_mov_b32_e32 v102, v0
	v_mov_b32_e32 v103, v0
	v_mov_b32_e32 v112, v0
	v_mov_b32_e32 v113, v0
	v_mov_b32_e32 v114, v0
	v_mov_b32_e32 v115, v0
	v_mov_b32_e32 v116, v0
	v_mov_b32_e32 v117, v0
	v_mov_b32_e32 v118, v0
	v_mov_b32_e32 v119, v0
	v_mov_b32_e32 v120, v0
	v_mov_b32_e32 v121, v0
	v_mov_b32_e32 v122, v0
	v_mov_b32_e32 v123, v0
	v_mov_b32_e32 v124, v0
	v_mov_b32_e32 v125, v0
	v_mov_b32_e32 v126, v0
	v_mov_b32_e32 v127, v0
	v_mov_b32_e32 v128, v0
	v_mov_b32_e32 v129, v0
	v_mov_b32_e32 v130, v0
	v_mov_b32_e32 v131, v0
	v_mov_b32_e32 v132, v0
	v_mov_b32_e32 v133, v0
	v_mov_b32_e32 v134, v0
	v_mov_b32_e32 v135, v0
	.p2align 6

; template <class Epi, class Sched, bool ALIGN_EPI = false, bool SP2 = false>
; __device__ __forceinline__ void gemm_phase(PG8_LAS unsigned char* lds, const Gemm g, const Sched& S, const Epi& E, int tid_in) {
;     ...
;         const bool has_next = S.next(ui + 1, nxt);
;         const char* nA = has_next ? (const char*)g.A + (size_t)nxt.pm * tstep : cA; const char* nB = has_next ? (const char*)g.Bt + (size_t)nxt.pn * tstep : cB;
;         for (int t = 0; t < nt; t += 2) {
;             const bool last = (t == nt - 2);
;             const char* a1 = cA + (size_t)(t + 1) * kstep;
;             const char* a2 = last ? nA : cA + (size_t)(t + 2) * kstep; const char* b2 = last ? nB : cB + (size_t)(t + 2) * kstep;
;             const char* a3 = a2 + kstep; const char* b3 = b2 + kstep;
;     ...
; #pragma unroll
;         for (int a = 0; a < 2; ++a)
; #pragma unroll
;             for (int b = 0; b < 2; ++b)
; #pragma unroll
;                 for (int m = 0; m < 4; ++m)
; #pragma unroll
;                     for (int n = 0; n < 2; ++n) acc[a][b][m][n] = (f32x4){0.f, 0.f, 0.f, 0.f};
.LBB0_483:
	s_ashr_i32 s21, s20, 31
	s_lshl_b64 s[22:23], s[20:21], 20
	s_add_u32 s22, s34, s22
	s_addc_u32 s23, s35, s23
	s_and_b64 s[24:25], s[0:1], exec
	s_cselect_b32 s21, s23, s37
	s_cselect_b32 s55, s22, s36
	s_ashr_i32 s19, s18, 31
	s_lshl_b64 s[24:25], s[18:19], 20
	s_add_u32 s24, s42, s24
	s_addc_u32 s25, s43, s25
	s_and_b64 s[40:41], s[0:1], exec
	s_cselect_b32 s19, s25, s39
	s_cselect_b32 s56, s24, s38
	s_add_u32 s36, s36, 0x80080
	s_addc_u32 s37, s37, 0
	s_add_u32 s57, s38, 0x100
	v_mov_b32_e32 v0, 0
	s_addc_u32 s58, s39, 0
	s_mov_b32 s59, -2
	v_mov_b32_e32 v1, v0
	v_mov_b32_e32 v2, v0
	v_mov_b32_e32 v3, v0
	v_mov_b32_e32 v4, v0
	v_mov_b32_e32 v5, v0
	v_mov_b32_e32 v6, v0
	v_mov_b32_e32 v7, v0
	v_mov_b32_e32 v16, v0
	v_mov_b32_e32 v17, v0
	v_mov_b32_e32 v18, v0
	v_mov_b32_e32 v19, v0
	v_mov_b32_e32 v20, v0
	v_mov_b32_e32 v21, v0
	v_mov_b32_e32 v22, v0
	v_mov_b32_e32 v23, v0
	v_mov_b32_e32 v32, v0
	v_mov_b32_e32 v33, v0
	v_mov_b32_e32 v34, v0
	v_mov_b32_e32 v35, v0
	v_mov_b32_e32 v36, v0
	v_mov_b32_e32 v37, v0
	v_mov_b32_e32 v38, v0
	v_mov_b32_e32 v39, v0
	v_mov_b32_e32 v48, v0
	v_mov_b32_e32 v49, v0
	v_mov_b32_e32 v50, v0
	v_mov_b32_e32 v51, v0
	v_mov_b32_e32 v52, v0
	v_mov_b32_e32 v53, v0
	v_mov_b32_e32 v54, v0
	v_mov_b32_e32 v55, v0
	v_mov_b32_e32 v8, v0
	v_mov_b32_e32 v9, v0
	v_mov_b32_e32 v10, v0
	v_mov_b32_e32 v11, v0
	v_mov_b32_e32 v12, v0
	v_mov_b32_e32 v13, v0
	v_mov_b32_e32 v14, v0
	v_mov_b32_e32 v15, v0
	v_mov_b32_e32 v24, v0
	v_mov_b32_e32 v25, v0
	v_mov_b32_e32 v26, v0
	v_mov_b32_e32 v27, v0
	v_mov_b32_e32 v28, v0
	v_mov_b32_e32 v29, v0
	v_mov_b32_e32 v30, v0
	v_mov_b32_e32 v31, v0
	v_mov_b32_e32 v40, v0
	v_mov_b32_e32 v41, v0
	v_mov_b32_e32 v42, v0
	v_mov_b32_e32 v43, v0
	v_mov_b32_e32 v44, v0
	v_mov_b32_e32 v45, v0
	v_mov_b32_e32 v46, v0
	v_mov_b32_e32 v47, v0
	v_mov_b32_e32 v56, v0
	v_mov_b32_e32 v57, v0
	v_mov_b32_e32 v58, v0
	v_mov_b32_e32 v59, v0
	v_mov_b32_e32 v60, v0
	v_mov_b32_e32 v61, v0
	v_mov_b32_e32 v62, v0
	v_mov_b32_e32 v63, v0
	v_mov_b32_e32 v64, v0
	v_mov_b32_e32 v65, v0
	v_mov_b32_e32 v66, v0
	v_mov_b32_e32 v67, v0
	v_mov_b32_e32 v68, v0
	v_mov_b32_e32 v69, v0
	v_mov_b32_e32 v70, v0
	v_mov_b32_e32 v71, v0
	v_mov_b32_e32 v80, v0
	v_mov_b32_e32 v81, v0
	v_mov_b32_e32 v82, v0
	v_mov_b32_e32 v83, v0
	v_mov_b32_e32 v84, v0
	v_mov_b32_e32 v85, v0
	v_mov_b32_e32 v86, v0
	v_mov_b32_e32 v87, v0
	v_mov_b32_e32 v96, v0
	v_mov_b32_e32 v97, v0
	v_mov_b32_e32 v98, v0
	v_mov_b32_e32 v99, v0
	v_mov_b32_e32 v100, v0
	v_mov_b32_e32 v101, v0
	v_mov_b32_e32 v102, v0
	v_mov_b32_e32 v103, v0
	v_mov_b32_e32 v112, v0
	v_mov_b32_e32 v113, v0
	v_mov_b32_e32 v114, v0
	v_mov_b32_e32 v115, v0
	v_mov_b32_e32 v116, v0
	v_mov_b32_e32 v117, v0
	v_mov_b32_e32 v118, v0
	v_mov_b32_e32 v119, v0
	v_mov_b32_e32 v72, v0
	v_mov_b32_e32 v73, v0
	v_mov_b32_e32 v74, v0
	v_mov_b32_e32 v75, v0
	v_mov_b32_e32 v76, v0
	v_mov_b32_e32 v77, v0
	v_mov_b32_e32 v78, v0
	v_mov_b32_e32 v79, v0
	v_mov_b32_e32 v88, v0
	v_mov_b32_e32 v89, v0
	v_mov_b32_e32 v90, v0
	v_mov_b32_e32 v91, v0
	v_mov_b32_e32 v92, v0
	v_mov_b32_e32 v93, v0
	v_mov_b32_e32 v94, v0
	v_mov_b32_e32 v95, v0
	v_mov_b32_e32 v104, v0
	v_mov_b32_e32 v105, v0
	v_mov_b32_e32 v106, v0
	v_mov_b32_e32 v107, v0
	v_mov_b32_e32 v108, v0
	v_mov_b32_e32 v109, v0
	v_mov_b32_e32 v110, v0
	v_mov_b32_e32 v111, v0
	v_mov_b32_e32 v120, v0
	v_mov_b32_e32 v121, v0
	v_mov_b32_e32 v122, v0
	v_mov_b32_e32 v123, v0
	v_mov_b32_e32 v124, v0
	v_mov_b32_e32 v125, v0
	v_mov_b32_e32 v126, v0
	v_mov_b32_e32 v127, v0
	.p2align 6
